# mixer work queue: 36-tile GQA items claimed before the differential items (LPT order), HGRN units still first
# speedup vs baseline: 1.0033x; 1.0033x over previous
; DI int tidx() { int t = threadIdx.x; asm volatile("" : "+v"(t)); return t; }
; DI void phase_mix(const P& p, int l, int rep, char* lds) {
;     ...
;   while (true) {
;     if (tidx() == 0) s_item = atomicAdd(&p.ctr[l + 2 * rep], 1);
;     __syncthreads();
;     int it = __builtin_amdgcn_readfirstlane(s_item);
;     __syncthreads();
;     if (it >= nitems) break;
;     if (it < 64) {
;       hgrn_unit(p, l, it, lds);
;       continue;
;     }
;     it -= 64;
;     int mode, b, hq, qb, sq0, sq1, sk, sv, qtok0, ka0, na, kb0 = 2048, nb = 0, yrow0, ycol0;
;     bool window = false, has_sink = false, isctx = false;
;     int kind;
;     if (it < 512) { kind = 0; b = it >> 5; hq = (it >> 3) & 3; qb = it & 7; }
;     else if (it < 768) { it -= 512; kind = 1; b = it >> 4; hq = (it >> 3) & 1; qb = it & 7; }
;     else if (it < 1024) { it -= 768; kind = 2; b = it >> 4; hq = (it >> 3) & 1; qb = it & 7; }
;     else if (it < 1088) { it -= 1024; kind = 0; isctx = true; b = it >> 2; hq = it & 3; qb = 0; }
;     else if (it < 1120) { it -= 1088; kind = 1; isctx = true; b = it >> 1; hq = it & 1; qb = 0; }
;     else { it -= 1120; kind = 2; isctx = true; b = it >> 1; hq = it & 1; qb = 0; }
.LBB0_821:
	s_or_b64 exec, exec, s[40:41]
	s_waitcnt lgkmcnt(0)
	s_barrier
	ds_read_b32 v0, v1 offset:16
	s_mov_b64 s[40:41], -1
	s_waitcnt lgkmcnt(0)
	s_barrier
	v_readfirstlane_b32 s26, v0
	s_cmp_ge_i32 s26, s59
	s_cbranch_scc1 .LBB0_816
	s_cmp_gt_i32 s26, 63
	s_cbranch_scc0 .LBB0_899
	s_cmpk_gt_u32 s26, 0x33f
	s_cbranch_scc1 .Llpt_done
	s_movk_i32 s2, 0xff00
	s_cmpk_lt_u32 s26, 0x140
	s_cselect_b32 s2, 0x200, s2
	s_add_i32 s26, s26, s2
.Llpt_done:
	s_cmpk_gt_u32 s26, 0x23f
	s_mov_b64 s[44:45], -1
	s_cbranch_scc0 .LBB0_840
	s_cmpk_gt_u32 s26, 0x33f
	s_cbranch_scc0 .LBB0_837
	s_mov_b64 s[46:47], -1
	s_cmpk_gt_u32 s26, 0x43f
	s_cbranch_scc0 .LBB0_834
	s_cmpk_gt_u32 s26, 0x47f
	s_mov_b64 s[40:41], -1
	s_cbranch_scc0 .LBB0_832
	s_cmpk_gt_u32 s26, 0x49f
	s_mov_b64 s[42:43], -1
	s_cbranch_scc0 .LBB0_829
	s_add_i32 s2, s26, 0xfffffb60
	s_lshr_b32 s2, s2, 1
	s_mov_b64 s[44:45], 0
